# GLA chain loop: one static s_setprio 1 for waves 4-7 before the loop (reset after), on top of counted LDS waits in phase A
# baseline (speedup 1.0000x reference)
; #define LAS __attribute__((address_space(3)))
; __device__ __forceinline__ int opaque_tid() { int t = threadIdx.x; asm volatile("" : "+v"(t)); return t; }
; #define GLA_VT(dst, cc) do { const size_t _ix = ((size_t)b * NCH + (cc)) * 4 + h; \
;         _Pragma("unroll") for (int _ks = 0; _ks < 2; ++_ks) dst[_ks] = *(const bf16x8*)(VTg + _ix * 16384 + (size_t)(e0w + fr) * 64 + _ks * 32 + fq * 8); } while (0)
; __device__ __forceinline__ void gla_prompt_unit(const Ctx& P, int l, int b, int h, int eh, LAS unsigned char* lds) {
;     const int tid = opaque_tid(), lane = tid & 63, w = __builtin_amdgcn_readfirstlane(tid >> 6), fr = lane & 15, fq = lane >> 4;
;     constexpr int QS = 256, ES = 128, KS = 144, BUFB = 3 * 16384, A_OFF = 3 * BUFB, DEC_OFF = A_OFF + 64 * KS;
;     const bf16_t* Z = (const bf16_t*)(P.ws + WS_Z); bf16_t* OG = (bf16_t*)(P.ws + WS_OG);
;     const bf16_t* QDg = (const bf16_t*)(P.ws + WS_QD); const bf16_t* KDg = (const bf16_t*)(P.ws + WS_KD); const bf16_t* KETg = (const bf16_t*)(P.ws + WS_KET); const bf16_t* VTg = (const bf16_t*)(P.ws + WS_VT);
;     const float* DEC = (const float*)(P.ws + WS_DEC); float* GSS = (float*)(P.ws + WS_GSS);
;     const int e0w = eh * 128 + 16 * w;
;     LAS unsigned char* Abuf = lds + A_OFF; LAS float* DECL = (LAS float*)(lds + DEC_OFF);
;     f32x4 S[8];
; #pragma unroll
;     for (int dt = 0; dt < 8; ++dt) S[dt] = (f32x4){0.f, 0.f, 0.f, 0.f};
;     bf16x8 vt[2], vtA[2], vtB[2];
;     const int grp = w >> 2;
;     ...
;     GLA_VT(vtA, 0); GLA_VT(vtB, 1);
;     float d1 = 0.f;
;     if (tid < 128) { DECL[tid] = DEC[((size_t)b * NCH) * 512 + h * 128 + tid]; d1 = DEC[((size_t)b * NCH + 1) * 512 + h * 128 + tid]; }
;     GLA_DMA(0, 0, w, 8, 2); GLA_DMA(1, 1, w, 8, 2);
;     asm volatile("s_waitcnt vmcnt(0)" ::: "memory");
;     __syncthreads();
;     int bufc = 0;
.LBB0_577:
	s_or_b64 exec, exec, s[14:15]
	s_mul_i32 s14, s0, 0x210000
	s_lshl_b32 s22, s30, 14
	s_or_b32 s14, s14, s22
	s_mul_hi_i32 s15, s0, 0x210000
	s_or_b32 s14, s14, s12
	s_add_i32 s63, s12, 0
	v_lshl_add_u64 v[76:77], s[14:15], 0, v[0:1]
	s_mul_i32 s12, s0, 0x420000
	s_lshl_b32 s14, s30, 15
	s_or_b32 s14, s12, s14
	s_or_b32 s12, s61, s13
	s_mul_hi_i32 s15, s0, 0x420000
	s_add_u32 s12, s12, 0x2dd21800
	v_mul_u32_u24_e32 v12, 0x90, v72
	s_waitcnt lgkmcnt(0)
	v_mul_u32_u24_e32 v13, 0x90, v73
	v_mul_u32_u24_e32 v14, 0x90, v82
	v_lshl_add_u64 v[10:11], s[14:15], 0, v[66:67]
	v_mov_b32_e32 v65, v1
	s_addc_u32 s13, s60, 0
	v_lshl_add_u64 v[78:79], v[10:11], 0, v[64:65]
	s_mov_b32 s61, 2
	v_lshl_add_u64 v[80:81], v[62:63], 2, s[12:13]
	v_add_u32_e32 v116, s34, v82
	s_mov_b32 s22, 1
	s_mov_b32 s68, 0
	v_add_u32_e32 v113, v69, v12
	v_add_u32_e32 v112, v69, v13
	v_add_u32_e32 v0, v70, v14
	v_readfirstlane_b32 s86, v188
	s_nop 3
	s_lshr_b32 s86, s86, 6
	s_cmp_ge_u32 s86, 4
	s_cbranch_scc0 .Lchain_prio_done
	s_setprio 1
.Lchain_prio_done:
	s_barrier

; __device__ __forceinline__ void gla_prompt_unit(const Ctx& P, int l, int b, int h, int eh, LAS unsigned char* lds) {
;     ...
;         { bf16x8 ka[2][4], qv[2][4];
; #pragma unroll
;           for (int ii = 0; ii < 2; ++ii) { const int idx = 2 * w + ii, si = idx >> 2, ti = idx & 3;
; #pragma unroll
;               for (int ks = 0; ks < 4; ++ks) { const int sw = ((ks * 4 + fq) ^ fr) * 16; ka[ii][ks] = *(const LAS bf16x8*)(kb + (16 * si + fr) * QS + sw); qv[ii][ks] = *(const LAS bf16x8*)(qb + (16 * ti + fr) * QS + sw); } }
;           __builtin_amdgcn_sched_barrier(0);
;           f32x4 acc[2];
; #pragma unroll
;           for (int ii = 0; ii < 2; ++ii) acc[ii] = (f32x4){0.f, 0.f, 0.f, 0.f};
; #pragma unroll
;           for (int ks = 0; ks < 4; ++ks)
; #pragma unroll
;               for (int ii = 0; ii < 2; ++ii) acc[ii] = MFMA16(ka[ii][ks], qv[ii][ks], acc[ii]);
; #pragma unroll
;           for (int ii = 0; ii < 2; ++ii) { const int idx = 2 * w + ii, si = idx >> 2, ti = idx & 3;
;               const int t = 16 * ti + fr;
;               float a0 = acc[ii][0], a1 = acc[ii][1], a2 = acc[ii][2], a3 = acc[ii][3]; const int s0 = 16 * si + fq * 4;
;               if (s0 + 0 > t) a0 = 0.f; if (s0 + 1 > t) a1 = 0.f; if (s0 + 2 > t) a2 = 0.f; if (s0 + 3 > t) a3 = 0.f;
;               u32x2 ow; ow.x = pk2(a0, a1); ow.y = pk2(a2, a3);
;               *(LAS u32x2*)(Abuf + t * KS + s0 * 2) = ow; } }
;         __syncthreads();
;         f32x4 o[4];
;         { bf16x8 af[2][4]; u32x2 q0[4][4], q1[4][4];
; #pragma unroll
;           for (int ks = 0; ks < 2; ++ks)
; #pragma unroll
;               for (int tt = 0; tt < 4; ++tt) af[ks][tt] = *(const LAS bf16x8*)(Abuf + (16 * tt + fr) * KS + ks * 64 + fq * 16);
; #pragma unroll
;           for (int ks = 0; ks < 4; ++ks)
; #pragma unroll
;               for (int tt = 0; tt < 4; ++tt) { q0[ks][tt] = *(const LAS u32x2*)(qb + (16 * tt + fr) * QS + (((4 * ks + (fq >> 1)) ^ fr) * 16) + 8 * (fq & 1)); q1[ks][tt] = *(const LAS u32x2*)(qb + (16 * tt + fr) * QS + (((4 * ks + 2 + (fq >> 1)) ^ fr) * 16) + 8 * (fq & 1)); }
;           bf16x8 sa[4];
; #pragma unroll
;           for (int ks = 0; ks < 4; ++ks) { u32x4 pw; pw.x = pk2(S[2 * ks][0], S[2 * ks][1]); pw.y = pk2(S[2 * ks][2], S[2 * ks][3]); pw.z = pk2(S[2 * ks + 1][0], S[2 * ks + 1][1]); pw.w = pk2(S[2 * ks + 1][2], S[2 * ks + 1][3]); sa[ks] = __builtin_bit_cast(bf16x8, pw); }
.LBB0_596:
	s_setprio 0
	s_mul_i32 s22, s60, 0xc000
	s_add_i32 s22, s22, 0
	v_add_u32_e32 v80, s22, v90
	v_add_u32_e32 v76, s22, v89
	v_add_u32_e32 v77, s28, v80
	v_add_u32_e32 v18, v76, v91
	v_add_u32_e32 v22, v77, v91
	v_add_u32_e32 v58, v76, v92
	v_add_u32_e32 v62, v77, v92
	v_add_u32_e32 v66, v76, v93
	v_add_u32_e32 v70, v77, v93
	v_add_u32_e32 v76, v76, v94
	v_add_u32_e32 v81, v77, v94
	ds_read_b128 v[18:21], v18 offset:16384
	ds_read_b128 v[22:25], v22
	ds_read_b128 v[58:61], v58 offset:16384
	ds_read_b128 v[62:65], v62
	ds_read_b128 v[66:69], v66 offset:16384
	ds_read_b128 v[70:73], v70
	ds_read_b128 v[76:79], v76 offset:16384
	ds_read_b128 v[116:119], v81
	v_add_u32_e32 v81, s29, v80
	v_add_u32_e32 v111, v81, v91
	v_add_u32_e32 v124, v81, v92
	ds_read_b128 v[120:123], v111
	ds_read_b128 v[124:127], v124
	v_add_u32_e32 v111, v81, v93
	v_add_u32_e32 v81, v81, v94
	ds_read_b128 v[142:145], v111
	ds_read_b128 v[146:149], v81
	s_waitcnt lgkmcnt(10)
	v_mfma_f32_16x16x32_bf16 v[22:25], v[18:21], v[22:25], 0
	v_add3_u32 v81, v80, v105, v88
	v_add3_u32 v111, v80, v103, v88
	v_cvt_pk_bf16_f32 v216, v54, v55
	s_waitcnt lgkmcnt(3)
	v_mfma_f32_16x16x32_bf16 v[18:21], v[18:21], v[120:123], 0
	v_cvt_pk_bf16_f32 v217, v56, v57
	v_cvt_pk_bf16_f32 v218, v50, v51
	v_cvt_pk_bf16_f32 v219, v52, v53
	v_mfma_f32_16x16x32_bf16 v[22:25], v[58:61], v[62:65], v[22:25]
	v_cvt_pk_bf16_f32 v220, v46, v47
	v_cvt_pk_bf16_f32 v221, v48, v49
	v_cvt_pk_bf16_f32 v222, v42, v43
	s_waitcnt lgkmcnt(2)
	v_mfma_f32_16x16x32_bf16 v[18:21], v[58:61], v[124:127], v[18:21]
	v_cvt_pk_bf16_f32 v223, v44, v45
	v_cvt_pk_bf16_f32 v224, v38, v39
	v_cvt_pk_bf16_f32 v225, v40, v41
	v_mfma_f32_16x16x32_bf16 v[22:25], v[66:69], v[70:73], v[22:25]
	v_cvt_pk_bf16_f32 v226, v34, v35
	v_cvt_pk_bf16_f32 v227, v36, v37
	v_cvt_pk_bf16_f32 v228, v30, v31
	s_waitcnt lgkmcnt(1)
	v_mfma_f32_16x16x32_bf16 v[18:21], v[66:69], v[142:145], v[18:21]
	v_cvt_pk_bf16_f32 v229, v32, v33
	v_cvt_pk_bf16_f32 v230, v26, v27
	v_cvt_pk_bf16_f32 v231, v28, v29
	v_mfma_f32_16x16x32_bf16 v[22:25], v[76:79], v[116:119], v[22:25]
	s_waitcnt lgkmcnt(0)
	v_mfma_f32_16x16x32_bf16 v[18:21], v[76:79], v[146:149], v[18:21]
	s_nop 5
	v_cndmask_b32_e64 v22, v22, 0, s[42:43]
	v_cndmask_b32_e64 v23, 0, v23, s[44:45]
	v_cndmask_b32_e64 v24, v24, 0, s[46:47]
	v_cndmask_b32_e64 v25, v25, 0, s[48:49]
	v_cndmask_b32_e64 v18, v18, 0, s[50:51]
	v_cndmask_b32_e64 v19, 0, v19, s[52:53]
	v_cndmask_b32_e64 v20, v20, 0, s[54:55]
	v_cndmask_b32_e64 v21, v21, 0, s[56:57]
	v_cvt_pk_bf16_f32 v22, v22, v23
	v_cvt_pk_bf16_f32 v23, v24, v25
	v_cvt_pk_bf16_f32 v18, v18, v19
	v_cvt_pk_bf16_f32 v19, v20, v21
	ds_write_b64 v113, v[22:23]
	ds_write_b64 v112, v[18:19]
	s_waitcnt lgkmcnt(0)
	s_barrier
	ds_read_b128 v[18:21], v0
	ds_read_b128 v[22:25], v0 offset:64
	ds_read_b128 v[58:61], v0 offset:2304
	ds_read_b128 v[62:65], v0 offset:2368
	ds_read_b128 v[66:69], v0 offset:4608
	ds_read_b128 v[70:73], v0 offset:4672
	ds_read_b128 v[76:79], v0 offset:6912
	ds_read_b128 v[116:119], v0 offset:6976
	ds_read2st64_b64 v[120:123], v81 offset1:8
	ds_read2st64_b64 v[124:127], v111 offset1:8
	ds_read2st64_b64 v[142:145], v81 offset0:16 offset1:24
	ds_read2st64_b64 v[146:149], v111 offset0:16 offset1:24
	v_add3_u32 v81, v80, v106, v88
	v_add3_u32 v111, v80, v104, v88
	ds_read2st64_b64 v[150:153], v81 offset1:8
	ds_read2st64_b64 v[154:157], v111 offset1:8
	ds_read2st64_b64 v[158:161], v81 offset0:16 offset1:24
	ds_read2st64_b64 v[162:165], v111 offset0:16 offset1:24
	v_add3_u32 v81, v80, v109, v88
	v_add3_u32 v111, v80, v107, v88
	ds_read2st64_b64 v[166:169], v81 offset1:8
	ds_read2st64_b64 v[170:173], v111 offset1:8
	ds_read2st64_b64 v[174:177], v81 offset0:16 offset1:24
	ds_read2st64_b64 v[178:181], v111 offset0:16 offset1:24
	v_add3_u32 v81, v80, v110, v88
	v_add3_u32 v80, v80, v108, v88
	ds_read2st64_b64 v[182:185], v81 offset1:8
	ds_read2st64_b64 v[204:207], v80 offset1:8
	ds_read2st64_b64 v[208:211], v81 offset0:16 offset1:24
	ds_read2st64_b64 v[212:215], v80 offset0:16 offset1:24
	s_waitcnt lgkmcnt(14)
	v_mfma_f32_16x16x32_bf16 v[18:21], v[6:9], v[18:21], 0
	v_mfma_f32_16x16x32_bf16 v[58:61], v[6:9], v[58:61], 0
	v_mfma_f32_16x16x32_bf16 v[66:69], v[6:9], v[66:69], 0
	v_mfma_f32_16x16x32_bf16 v[76:79], v[6:9], v[76:79], 0
	v_mfma_f32_16x16x32_bf16 v[18:21], v[2:5], v[22:25], v[18:21]
	v_mfma_f32_16x16x32_bf16 v[22:25], v[2:5], v[62:65], v[58:61]
	v_mfma_f32_16x16x32_bf16 v[58:61], v[2:5], v[70:73], v[66:69]
	v_mfma_f32_16x16x32_bf16 v[62:65], v[2:5], v[116:119], v[76:79]
	s_nop 2
	v_mov_b32_e32 v66, v120
	v_mov_b32_e32 v67, v121
	v_mov_b32_e32 v68, v124
	v_mov_b32_e32 v69, v125
	v_mov_b32_e32 v124, v122
	v_mov_b32_e32 v125, v123
	v_mfma_f32_16x16x32_bf16 v[18:21], v[216:219], v[66:69], v[18:21]
	s_waitcnt lgkmcnt(13)
	v_mov_b32_e32 v66, v142
	v_mov_b32_e32 v67, v143
	s_waitcnt lgkmcnt(12)
	v_mov_b32_e32 v68, v146
	v_mov_b32_e32 v69, v147
	v_mov_b32_e32 v146, v144
	v_mov_b32_e32 v147, v145
	v_mfma_f32_16x16x32_bf16 v[22:25], v[216:219], v[124:127], v[22:25]
	v_mfma_f32_16x16x32_bf16 v[58:61], v[216:219], v[66:69], v[58:61]
	s_waitcnt lgkmcnt(11)
	v_mov_b32_e32 v66, v150
	v_mov_b32_e32 v67, v151
	s_waitcnt lgkmcnt(10)
; #define LAS __attribute__((address_space(3)))
; #define MFMA16(a, b, c) __builtin_amdgcn_mfma_f32_16x16x32_bf16((a), (b), (c), 0, 0, 0)
; __device__ __forceinline__ void gla_prompt_unit(const Ctx& P, int l, int b, int h, int eh, LAS unsigned char* lds) {
;     ...
;           for (int ks = 0; ks < 2; ++ks)
; #pragma unroll
;               for (int tt = 0; tt < 4; ++tt) o[tt] = MFMA16(vt[ks], af[ks][tt], o[tt]);
; #pragma unroll
;           for (int ks = 0; ks < 4; ++ks)
; #pragma unroll
;               for (int tt = 0; tt < 4; ++tt) { u32x4 qw; qw.x = q0[ks][tt].x; qw.y = q0[ks][tt].y; qw.z = q1[ks][tt].x; qw.w = q1[ks][tt].y;
;                   o[tt] = MFMA16(sa[ks], __builtin_bit_cast(bf16x8, qw), o[tt]); } }
;         __builtin_amdgcn_sched_barrier(0);
;         { const LAS float* dp = DECL + bufc * 128; bf16x8 kf[8][2]; f32x4 dv[8];
; #pragma unroll
;           for (int dt = 0; dt < 8; ++dt) { dv[dt] = *(const LAS f32x4*)(dp + 16 * dt + fq * 4);
; #pragma unroll
;               for (int ks = 0; ks < 2; ++ks) kf[dt][ks] = *(const LAS bf16x8*)(eb + (16 * dt + fr) * ES + (((ks * 4 + fq) ^ (fr & 7)) * 16)); }
;           __builtin_amdgcn_sched_barrier(0);
; #pragma unroll
;           for (int dt = 0; dt < 8; ++dt) S[dt] = S[dt] * dv[dt];
; #pragma unroll
;           for (int ks = 0; ks < 2; ++ks)
; #pragma unroll
;               for (int dt = 0; dt < 8; ++dt) S[dt] = MFMA16(kf[dt][ks], vt[ks], S[dt]); }
;         __builtin_amdgcn_sched_barrier(0);
;         if (grp == ((c + 1) & 1)) asm volatile("s_waitcnt vmcnt(0)" ::: "memory");
	v_mov_b32_e32 v68, v154
	v_mfma_f32_16x16x32_bf16 v[62:65], v[216:219], v[146:149], v[62:65]
	v_mov_b32_e32 v69, v155
	v_mov_b32_e32 v154, v152
	v_mov_b32_e32 v155, v153
	v_mfma_f32_16x16x32_bf16 v[18:21], v[220:223], v[66:69], v[18:21]
	s_waitcnt lgkmcnt(9)
	v_mov_b32_e32 v66, v158
	v_mov_b32_e32 v67, v159
	s_waitcnt lgkmcnt(8)
	v_mov_b32_e32 v68, v162
	v_mov_b32_e32 v69, v163
	v_mov_b32_e32 v162, v160
	v_mov_b32_e32 v163, v161
	v_mfma_f32_16x16x32_bf16 v[22:25], v[220:223], v[154:157], v[22:25]
	v_mfma_f32_16x16x32_bf16 v[58:61], v[220:223], v[66:69], v[58:61]
	s_waitcnt lgkmcnt(7)
	v_mov_b32_e32 v66, v166
	v_mov_b32_e32 v67, v167
	s_waitcnt lgkmcnt(6)
	v_mov_b32_e32 v68, v170
	v_mfma_f32_16x16x32_bf16 v[62:65], v[220:223], v[162:165], v[62:65]
	v_mov_b32_e32 v69, v171
	v_mov_b32_e32 v170, v168
	v_mov_b32_e32 v171, v169
	v_mfma_f32_16x16x32_bf16 v[18:21], v[224:227], v[66:69], v[18:21]
	s_waitcnt lgkmcnt(5)
	v_mov_b32_e32 v66, v174
	v_mov_b32_e32 v67, v175
	s_waitcnt lgkmcnt(4)
	v_mov_b32_e32 v68, v178
	v_mov_b32_e32 v69, v179
	v_mov_b32_e32 v178, v176
	v_mov_b32_e32 v179, v177
	v_mfma_f32_16x16x32_bf16 v[22:25], v[224:227], v[170:173], v[22:25]
	v_mfma_f32_16x16x32_bf16 v[58:61], v[224:227], v[66:69], v[58:61]
	v_mfma_f32_16x16x32_bf16 v[76:79], v[224:227], v[178:181], v[62:65]
	s_waitcnt lgkmcnt(3)
	s_nop 1
	v_mov_b32_e32 v62, v182
	v_mov_b32_e32 v63, v183
	s_waitcnt lgkmcnt(2)
	v_mov_b32_e32 v64, v204
	v_mov_b32_e32 v65, v205
	v_mov_b32_e32 v204, v184
	v_mov_b32_e32 v205, v185
	v_mfma_f32_16x16x32_bf16 v[70:73], v[228:231], v[62:65], v[18:21]
	s_waitcnt lgkmcnt(1)
	s_nop 1
	v_mov_b32_e32 v18, v208
	v_mov_b32_e32 v19, v209
	s_waitcnt lgkmcnt(0)
	v_mov_b32_e32 v20, v212
	v_mov_b32_e32 v21, v213
	v_mov_b32_e32 v212, v210
	v_mov_b32_e32 v213, v211
	v_mfma_f32_16x16x32_bf16 v[66:69], v[228:231], v[204:207], v[22:25]
	v_mfma_f32_16x16x32_bf16 v[62:65], v[228:231], v[18:21], v[58:61]
	v_mfma_f32_16x16x32_bf16 v[58:61], v[228:231], v[212:215], v[76:79]
	s_nop 2
	v_add_u32_e32 v76, s22, v100
	v_add_u32_e32 v120, s22, v101
	v_add_u32_e32 v128, s22, v102
	v_lshl_add_u32 v80, s60, 9, v85
	v_add_u32_e32 v18, s22, v99
	v_add_u32_e32 v77, v76, v97
	v_add_u32_e32 v116, v76, v98
	v_add_u32_e32 v121, v120, v97
	v_add_u32_e32 v124, v120, v98
	v_add_u32_e32 v129, v128, v97
	v_add_u32_e32 v81, v18, v97
	v_add_u32_e32 v111, v18, v98
	ds_read_b128 v[18:21], v80
	ds_read_b128 v[22:25], v80 offset:64
	ds_read_b128 v[76:79], v77 offset:32768
	ds_read_b128 v[116:119], v116 offset:32768
	ds_read_b128 v[120:123], v121 offset:32768
	ds_read_b128 v[124:127], v124 offset:32768
	ds_read_b128 v[142:145], v80 offset:128
	ds_read_b128 v[146:149], v80 offset:192
	v_add_u32_e32 v128, v128, v98
	ds_read_b128 v[150:153], v129 offset:32768
	ds_read_b128 v[154:157], v128 offset:32768
	ds_read_b128 v[158:161], v81 offset:32768
	ds_read_b128 v[162:165], v81 offset:40960
	ds_read_b128 v[166:169], v80 offset:256
	ds_read_b128 v[170:173], v80 offset:320
	ds_read_b128 v[174:177], v111 offset:40960
	ds_read_b128 v[178:181], v111 offset:43008
	ds_read_b128 v[182:185], v81 offset:43008
	ds_read_b128 v[204:207], v81 offset:45056
	ds_read_b128 v[208:211], v80 offset:384
	ds_read_b128 v[212:215], v80 offset:448
	ds_read_b128 v[216:219], v111 offset:32768
	ds_read_b128 v[220:223], v81 offset:47104
	ds_read_b128 v[224:227], v111 offset:45056
	ds_read_b128 v[228:231], v111 offset:47104
	s_waitcnt lgkmcnt(14)
	v_pk_mul_f32 v[20:21], v[56:57], v[20:21]
	v_pk_mul_f32 v[18:19], v[54:55], v[18:19]
	v_pk_mul_f32 v[24:25], v[52:53], v[24:25]
	v_pk_mul_f32 v[22:23], v[50:51], v[22:23]
	v_pk_mul_f32 v[48:49], v[48:49], v[144:145]
	v_pk_mul_f32 v[46:47], v[46:47], v[142:143]
	v_pk_mul_f32 v[44:45], v[44:45], v[148:149]
	v_pk_mul_f32 v[42:43], v[42:43], v[146:147]
	s_waitcnt lgkmcnt(11)
	v_pk_mul_f32 v[40:41], v[40:41], v[168:169]
	v_pk_mul_f32 v[38:39], v[38:39], v[166:167]
	s_waitcnt lgkmcnt(10)
	v_pk_mul_f32 v[36:37], v[36:37], v[172:173]
	v_pk_mul_f32 v[34:35], v[34:35], v[170:171]
	s_waitcnt lgkmcnt(5)
	v_pk_mul_f32 v[32:33], v[32:33], v[210:211]
	v_pk_mul_f32 v[30:31], v[30:31], v[208:209]
	s_waitcnt lgkmcnt(4)
	v_pk_mul_f32 v[28:29], v[28:29], v[214:215]
	v_pk_mul_f32 v[26:27], v[26:27], v[212:213]
	v_mfma_f32_16x16x32_bf16 v[18:21], v[158:161], v[6:9], v[18:21]
	v_mfma_f32_16x16x32_bf16 v[22:25], v[76:79], v[6:9], v[22:25]
	v_mfma_f32_16x16x32_bf16 v[46:49], v[120:123], v[6:9], v[46:49]
	v_mfma_f32_16x16x32_bf16 v[42:45], v[150:153], v[6:9], v[42:45]
	v_mfma_f32_16x16x32_bf16 v[50:53], v[162:165], v[6:9], v[38:41]
	v_mfma_f32_16x16x32_bf16 v[54:57], v[182:185], v[6:9], v[34:37]
	v_mfma_f32_16x16x32_bf16 v[76:79], v[204:207], v[6:9], v[30:33]
	s_waitcnt lgkmcnt(2)
	v_mfma_f32_16x16x32_bf16 v[120:123], v[220:223], v[6:9], v[26:29]
	v_mfma_f32_16x16x32_bf16 v[38:41], v[216:219], v[2:5], v[18:21]
	v_mfma_f32_16x16x32_bf16 v[34:37], v[116:119], v[2:5], v[22:25]
	v_mfma_f32_16x16x32_bf16 v[30:33], v[124:127], v[2:5], v[46:49]
	v_mfma_f32_16x16x32_bf16 v[26:29], v[154:157], v[2:5], v[42:45]
	v_mfma_f32_16x16x32_bf16 v[22:25], v[174:177], v[2:5], v[50:53]
	v_mfma_f32_16x16x32_bf16 v[18:21], v[178:181], v[2:5], v[54:57]
	s_waitcnt lgkmcnt(1)
	v_mfma_f32_16x16x32_bf16 v[6:9], v[224:227], v[2:5], v[76:79]
	s_waitcnt lgkmcnt(0)
	v_mfma_f32_16x16x32_bf16 v[2:5], v[228:231], v[2:5], v[120:123]
	s_andn2_b64 vcc, exec, s[14:15]
	s_cbranch_vccnz .LBB0_598
	s_waitcnt vmcnt(0)
